# sgu item statistics pass: 32 serialized 16-byte loads per thread -> 2 batches of 16 (same arithmetic order)
# baseline (speedup 1.0000x reference)
.LBB0_428:
	v_lshl_add_u64 v[6:7], v[2:3], 0, s[8:9]
	v_add_co_u32_e32 v10, vcc, 0x4ac1000, v6
	s_add_u32 s8, s8, 0x100
	s_nop 0
	v_addc_co_u32_e32 v11, vcc, 0, v7, vcc
	s_addc_u32 s9, s9, 0
	global_load_dwordx4 v[20:23], v[10:11], off
	global_load_dwordx4 v[24:27], v[10:11], off offset:16
	global_load_dwordx4 v[28:31], v[10:11], off offset:32
	global_load_dwordx4 v[32:35], v[10:11], off offset:48
	global_load_dwordx4 v[36:39], v[10:11], off offset:64
	global_load_dwordx4 v[40:43], v[10:11], off offset:80
	global_load_dwordx4 v[44:47], v[10:11], off offset:96
	global_load_dwordx4 v[48:51], v[10:11], off offset:112
	global_load_dwordx4 v[52:55], v[10:11], off offset:128
	global_load_dwordx4 v[56:59], v[10:11], off offset:144
	global_load_dwordx4 v[60:63], v[10:11], off offset:160
	global_load_dwordx4 v[64:67], v[10:11], off offset:176
	global_load_dwordx4 v[68:71], v[10:11], off offset:192
	global_load_dwordx4 v[72:75], v[10:11], off offset:208
	global_load_dwordx4 v[76:79], v[10:11], off offset:224
	global_load_dwordx4 v[80:83], v[10:11], off offset:240
	s_waitcnt vmcnt(15)
	v_lshlrev_b32_e32 v12, 16, v20
	v_lshlrev_b32_e32 v15, 16, v21
	v_and_b32_e32 v14, 0xffff0000, v20
	v_add_f32_e32 v5, v5, v12
	v_fmac_f32_e32 v4, v12, v12
	v_pk_mul_f32 v[16:17], v[14:15], v[14:15]
	v_add_f32_e32 v5, v5, v14
	v_add_f32_e32 v4, v16, v4
	v_add_f32_e32 v6, v5, v15
	v_add_f32_e32 v12, v17, v4
	v_lshlrev_b32_e32 v5, 16, v22
	v_and_b32_e32 v4, 0xffff0000, v21
	v_and_b32_e32 v13, 0xffff0000, v22
	v_add_f32_e32 v8, v6, v4
	v_pk_mul_f32 v[6:7], v[4:5], v[4:5]
	v_add_f32_e32 v5, v8, v5
	v_add_f32_e32 v4, v6, v12
	v_lshlrev_b32_e32 v6, 16, v23
	v_mov_b32_e32 v12, v6
	v_add_f32_e32 v14, v7, v4
	v_and_b32_e32 v7, 0xffff0000, v23
	v_pk_mul_f32 v[8:9], v[12:13], v[12:13]
	v_add_f32_e32 v4, v5, v13
	v_add_f32_e32 v5, v9, v14
	v_add_f32_e32 v8, v8, v5
	v_mov_b32_e32 v5, v7
	v_pk_mul_f32 v[12:13], v[6:7], v[6:7]
	v_pk_add_f32 v[4:5], v[4:5], v[6:7]
	v_mov_b32_e32 v9, v7
	v_pk_mov_b32 v[4:5], v[12:13], v[4:5] op_sel:[1,0]
	s_nop 0
	v_pk_add_f32 v[8:9], v[4:5], v[8:9]
	s_waitcnt vmcnt(14)
	v_lshlrev_b32_e32 v10, 16, v24
	v_lshlrev_b32_e32 v13, 16, v25
	v_and_b32_e32 v12, 0xffff0000, v24
	v_add_f32_e32 v9, v9, v10
	v_fmac_f32_e32 v8, v10, v10
	v_pk_mul_f32 v[14:15], v[12:13], v[12:13]
	v_add_f32_e32 v4, v9, v12
	v_add_f32_e32 v8, v14, v8
	v_add_f32_e32 v4, v4, v13
	v_add_f32_e32 v10, v15, v8
	v_lshlrev_b32_e32 v9, 16, v26
	v_and_b32_e32 v8, 0xffff0000, v25
	v_and_b32_e32 v11, 0xffff0000, v26
	v_add_f32_e32 v6, v4, v8
	v_pk_mul_f32 v[4:5], v[8:9], v[8:9]
	v_lshlrev_b32_e32 v8, 16, v27
	v_add_f32_e32 v4, v4, v10
	v_add_f32_e32 v6, v6, v9
	v_mov_b32_e32 v10, v8
	v_add_f32_e32 v5, v5, v4
	v_add_f32_e32 v4, v6, v11
	v_and_b32_e32 v9, 0xffff0000, v27
	v_pk_mul_f32 v[6:7], v[10:11], v[10:11]
	v_pk_mul_f32 v[10:11], v[8:9], v[8:9]
	v_add_f32_e32 v5, v7, v5
	v_add_f32_e32 v6, v6, v5
	v_mov_b32_e32 v5, v9
	v_pk_add_f32 v[4:5], v[4:5], v[8:9]
	v_mov_b32_e32 v7, v9
	v_pk_mov_b32 v[4:5], v[10:11], v[4:5] op_sel:[1,0]
	s_nop 0
	v_pk_add_f32 v[4:5], v[4:5], v[6:7]
	s_waitcnt vmcnt(13)
	v_lshlrev_b32_e32 v12, 16, v28
	v_lshlrev_b32_e32 v15, 16, v29
	v_and_b32_e32 v14, 0xffff0000, v28
	v_add_f32_e32 v5, v5, v12
	v_fmac_f32_e32 v4, v12, v12
	v_pk_mul_f32 v[16:17], v[14:15], v[14:15]
	v_add_f32_e32 v5, v5, v14
	v_add_f32_e32 v4, v16, v4
	v_add_f32_e32 v6, v5, v15
	v_add_f32_e32 v12, v17, v4
	v_lshlrev_b32_e32 v5, 16, v30
	v_and_b32_e32 v4, 0xffff0000, v29
	v_and_b32_e32 v13, 0xffff0000, v30
	v_add_f32_e32 v8, v6, v4
	v_pk_mul_f32 v[6:7], v[4:5], v[4:5]
	v_add_f32_e32 v5, v8, v5
	v_add_f32_e32 v4, v6, v12
	v_lshlrev_b32_e32 v6, 16, v31
	v_mov_b32_e32 v12, v6
	v_add_f32_e32 v14, v7, v4
	v_and_b32_e32 v7, 0xffff0000, v31
	v_pk_mul_f32 v[8:9], v[12:13], v[12:13]
	v_add_f32_e32 v4, v5, v13
	v_add_f32_e32 v5, v9, v14
	v_add_f32_e32 v8, v8, v5
	v_mov_b32_e32 v5, v7
	v_pk_mul_f32 v[12:13], v[6:7], v[6:7]
	v_pk_add_f32 v[4:5], v[4:5], v[6:7]
	v_mov_b32_e32 v9, v7
	v_pk_mov_b32 v[4:5], v[12:13], v[4:5] op_sel:[1,0]
	s_nop 0
	v_pk_add_f32 v[8:9], v[4:5], v[8:9]
	s_waitcnt vmcnt(12)
	v_lshlrev_b32_e32 v10, 16, v32
	v_lshlrev_b32_e32 v13, 16, v33
	v_and_b32_e32 v12, 0xffff0000, v32
	v_add_f32_e32 v9, v9, v10
	v_fmac_f32_e32 v8, v10, v10
	v_pk_mul_f32 v[14:15], v[12:13], v[12:13]
	v_add_f32_e32 v4, v9, v12
	v_add_f32_e32 v8, v14, v8
	v_add_f32_e32 v4, v4, v13
	v_add_f32_e32 v10, v15, v8
	v_lshlrev_b32_e32 v9, 16, v34
	v_and_b32_e32 v8, 0xffff0000, v33
	v_and_b32_e32 v11, 0xffff0000, v34
	v_add_f32_e32 v6, v4, v8
	v_pk_mul_f32 v[4:5], v[8:9], v[8:9]
	v_lshlrev_b32_e32 v8, 16, v35
	v_add_f32_e32 v4, v4, v10
	v_add_f32_e32 v6, v6, v9
	v_mov_b32_e32 v10, v8
	v_add_f32_e32 v5, v5, v4
	v_add_f32_e32 v4, v6, v11
	v_and_b32_e32 v9, 0xffff0000, v35
	v_pk_mul_f32 v[6:7], v[10:11], v[10:11]
	v_pk_mul_f32 v[10:11], v[8:9], v[8:9]
	v_add_f32_e32 v5, v7, v5
	v_add_f32_e32 v6, v6, v5
	v_mov_b32_e32 v5, v9
	v_pk_add_f32 v[4:5], v[4:5], v[8:9]
	v_mov_b32_e32 v7, v9
	v_pk_mov_b32 v[4:5], v[10:11], v[4:5] op_sel:[1,0]
	s_nop 0
	v_pk_add_f32 v[4:5], v[4:5], v[6:7]
	s_waitcnt vmcnt(11)
	v_lshlrev_b32_e32 v12, 16, v36
	v_lshlrev_b32_e32 v15, 16, v37
	v_and_b32_e32 v14, 0xffff0000, v36
	v_add_f32_e32 v5, v5, v12
	v_fmac_f32_e32 v4, v12, v12
	v_pk_mul_f32 v[16:17], v[14:15], v[14:15]
	v_add_f32_e32 v5, v5, v14
	v_add_f32_e32 v4, v16, v4
	v_add_f32_e32 v6, v5, v15
	v_add_f32_e32 v12, v17, v4
	v_lshlrev_b32_e32 v5, 16, v38
	v_and_b32_e32 v4, 0xffff0000, v37
	v_and_b32_e32 v13, 0xffff0000, v38
	v_add_f32_e32 v8, v6, v4
	v_pk_mul_f32 v[6:7], v[4:5], v[4:5]
	v_add_f32_e32 v5, v8, v5
	v_add_f32_e32 v4, v6, v12
	v_lshlrev_b32_e32 v6, 16, v39
	v_mov_b32_e32 v12, v6
	v_add_f32_e32 v14, v7, v4
	v_and_b32_e32 v7, 0xffff0000, v39
	v_pk_mul_f32 v[8:9], v[12:13], v[12:13]
	v_add_f32_e32 v4, v5, v13
	v_add_f32_e32 v5, v9, v14
	v_add_f32_e32 v8, v8, v5
	v_mov_b32_e32 v5, v7
	v_pk_mul_f32 v[12:13], v[6:7], v[6:7]
	v_pk_add_f32 v[4:5], v[4:5], v[6:7]
	v_mov_b32_e32 v9, v7
	v_pk_mov_b32 v[4:5], v[12:13], v[4:5] op_sel:[1,0]
	s_nop 0
	v_pk_add_f32 v[8:9], v[4:5], v[8:9]
	s_waitcnt vmcnt(10)
	v_lshlrev_b32_e32 v10, 16, v40
	v_lshlrev_b32_e32 v13, 16, v41
	v_and_b32_e32 v12, 0xffff0000, v40
	v_add_f32_e32 v9, v9, v10
	v_fmac_f32_e32 v8, v10, v10
	v_pk_mul_f32 v[14:15], v[12:13], v[12:13]
	v_add_f32_e32 v4, v9, v12
	v_add_f32_e32 v8, v14, v8
	v_add_f32_e32 v4, v4, v13
	v_add_f32_e32 v10, v15, v8
	v_lshlrev_b32_e32 v9, 16, v42
	v_and_b32_e32 v8, 0xffff0000, v41
	v_and_b32_e32 v11, 0xffff0000, v42
	v_add_f32_e32 v6, v4, v8
	v_pk_mul_f32 v[4:5], v[8:9], v[8:9]
	v_lshlrev_b32_e32 v8, 16, v43
	v_add_f32_e32 v4, v4, v10
	v_add_f32_e32 v6, v6, v9
	v_mov_b32_e32 v10, v8
	v_add_f32_e32 v5, v5, v4
	v_add_f32_e32 v4, v6, v11
	v_and_b32_e32 v9, 0xffff0000, v43
	v_pk_mul_f32 v[6:7], v[10:11], v[10:11]
	v_pk_mul_f32 v[10:11], v[8:9], v[8:9]
	v_add_f32_e32 v5, v7, v5
	v_add_f32_e32 v6, v6, v5
	v_mov_b32_e32 v5, v9
	v_pk_add_f32 v[4:5], v[4:5], v[8:9]
	v_mov_b32_e32 v7, v9
	v_pk_mov_b32 v[4:5], v[10:11], v[4:5] op_sel:[1,0]
	s_nop 0
	v_pk_add_f32 v[4:5], v[4:5], v[6:7]
	s_waitcnt vmcnt(9)
	v_lshlrev_b32_e32 v12, 16, v44
	v_lshlrev_b32_e32 v15, 16, v45
	v_and_b32_e32 v14, 0xffff0000, v44
	v_add_f32_e32 v5, v5, v12
	v_fmac_f32_e32 v4, v12, v12
	v_pk_mul_f32 v[16:17], v[14:15], v[14:15]
	v_add_f32_e32 v5, v5, v14
	v_add_f32_e32 v4, v16, v4
	v_add_f32_e32 v6, v5, v15
	v_add_f32_e32 v12, v17, v4
	v_lshlrev_b32_e32 v5, 16, v46
	v_and_b32_e32 v4, 0xffff0000, v45
	v_and_b32_e32 v13, 0xffff0000, v46
	v_add_f32_e32 v8, v6, v4
	v_pk_mul_f32 v[6:7], v[4:5], v[4:5]
	v_add_f32_e32 v5, v8, v5
	v_add_f32_e32 v4, v6, v12
	v_lshlrev_b32_e32 v6, 16, v47
	v_mov_b32_e32 v12, v6
	v_add_f32_e32 v14, v7, v4
	v_and_b32_e32 v7, 0xffff0000, v47
	v_pk_mul_f32 v[8:9], v[12:13], v[12:13]
	v_add_f32_e32 v4, v5, v13
	v_add_f32_e32 v5, v9, v14
	v_add_f32_e32 v8, v8, v5
	v_mov_b32_e32 v5, v7
	v_pk_mul_f32 v[12:13], v[6:7], v[6:7]
	v_pk_add_f32 v[4:5], v[4:5], v[6:7]
	v_mov_b32_e32 v9, v7
	v_pk_mov_b32 v[4:5], v[12:13], v[4:5] op_sel:[1,0]
	s_nop 0
	v_pk_add_f32 v[8:9], v[4:5], v[8:9]
	s_waitcnt vmcnt(8)
	v_lshlrev_b32_e32 v10, 16, v48
	v_lshlrev_b32_e32 v13, 16, v49
	v_and_b32_e32 v12, 0xffff0000, v48
	v_add_f32_e32 v9, v9, v10
	v_fmac_f32_e32 v8, v10, v10
	v_pk_mul_f32 v[14:15], v[12:13], v[12:13]
	v_add_f32_e32 v4, v9, v12
	v_add_f32_e32 v8, v14, v8
	v_add_f32_e32 v4, v4, v13
	v_add_f32_e32 v10, v15, v8
	v_lshlrev_b32_e32 v9, 16, v50
	v_and_b32_e32 v8, 0xffff0000, v49
	v_and_b32_e32 v11, 0xffff0000, v50
	v_add_f32_e32 v6, v4, v8
	v_pk_mul_f32 v[4:5], v[8:9], v[8:9]
	v_lshlrev_b32_e32 v8, 16, v51
	v_add_f32_e32 v4, v4, v10
	v_add_f32_e32 v6, v6, v9
	v_mov_b32_e32 v10, v8
	v_add_f32_e32 v5, v5, v4
	v_add_f32_e32 v4, v6, v11
	v_and_b32_e32 v9, 0xffff0000, v51
	v_pk_mul_f32 v[6:7], v[10:11], v[10:11]
	v_pk_mul_f32 v[10:11], v[8:9], v[8:9]
	v_add_f32_e32 v5, v7, v5
	v_add_f32_e32 v6, v6, v5
	v_mov_b32_e32 v5, v9
	v_pk_add_f32 v[4:5], v[4:5], v[8:9]
	v_mov_b32_e32 v7, v9
	v_pk_mov_b32 v[4:5], v[10:11], v[4:5] op_sel:[1,0]
	s_nop 0
	v_pk_add_f32 v[4:5], v[4:5], v[6:7]
	s_waitcnt vmcnt(7)
	v_lshlrev_b32_e32 v12, 16, v52
	v_lshlrev_b32_e32 v15, 16, v53
	v_and_b32_e32 v14, 0xffff0000, v52
	v_add_f32_e32 v5, v5, v12
	v_fmac_f32_e32 v4, v12, v12
	v_pk_mul_f32 v[16:17], v[14:15], v[14:15]
	v_add_f32_e32 v5, v5, v14
	v_add_f32_e32 v4, v16, v4
	v_add_f32_e32 v6, v5, v15
	v_add_f32_e32 v12, v17, v4
	v_lshlrev_b32_e32 v5, 16, v54
	v_and_b32_e32 v4, 0xffff0000, v53
	v_and_b32_e32 v13, 0xffff0000, v54
	v_add_f32_e32 v8, v6, v4
	v_pk_mul_f32 v[6:7], v[4:5], v[4:5]
	v_add_f32_e32 v5, v8, v5
	v_add_f32_e32 v4, v6, v12
	v_lshlrev_b32_e32 v6, 16, v55
	v_mov_b32_e32 v12, v6
	v_add_f32_e32 v14, v7, v4
	v_and_b32_e32 v7, 0xffff0000, v55
	v_pk_mul_f32 v[8:9], v[12:13], v[12:13]
	v_add_f32_e32 v4, v5, v13
	v_add_f32_e32 v5, v9, v14
	v_add_f32_e32 v8, v8, v5
	v_mov_b32_e32 v5, v7
	v_pk_mul_f32 v[12:13], v[6:7], v[6:7]
	v_pk_add_f32 v[4:5], v[4:5], v[6:7]
	v_mov_b32_e32 v9, v7
	v_pk_mov_b32 v[4:5], v[12:13], v[4:5] op_sel:[1,0]
	s_nop 0
	v_pk_add_f32 v[8:9], v[4:5], v[8:9]
	s_waitcnt vmcnt(6)
	v_lshlrev_b32_e32 v10, 16, v56
	v_lshlrev_b32_e32 v13, 16, v57
	v_and_b32_e32 v12, 0xffff0000, v56
	v_add_f32_e32 v9, v9, v10
	v_fmac_f32_e32 v8, v10, v10
	v_pk_mul_f32 v[14:15], v[12:13], v[12:13]
	v_add_f32_e32 v4, v9, v12
	v_add_f32_e32 v8, v14, v8
	v_add_f32_e32 v4, v4, v13
	v_add_f32_e32 v10, v15, v8
	v_lshlrev_b32_e32 v9, 16, v58
	v_and_b32_e32 v8, 0xffff0000, v57
	v_and_b32_e32 v11, 0xffff0000, v58
	v_add_f32_e32 v6, v4, v8
	v_pk_mul_f32 v[4:5], v[8:9], v[8:9]
	v_lshlrev_b32_e32 v8, 16, v59
	v_add_f32_e32 v4, v4, v10
	v_add_f32_e32 v6, v6, v9
	v_mov_b32_e32 v10, v8
	v_add_f32_e32 v5, v5, v4
	v_add_f32_e32 v4, v6, v11
	v_and_b32_e32 v9, 0xffff0000, v59
	v_pk_mul_f32 v[6:7], v[10:11], v[10:11]
	v_pk_mul_f32 v[10:11], v[8:9], v[8:9]
	v_add_f32_e32 v5, v7, v5
	v_add_f32_e32 v6, v6, v5
	v_mov_b32_e32 v5, v9
	v_pk_add_f32 v[4:5], v[4:5], v[8:9]
	v_mov_b32_e32 v7, v9
	v_pk_mov_b32 v[4:5], v[10:11], v[4:5] op_sel:[1,0]
	s_nop 0
	v_pk_add_f32 v[4:5], v[4:5], v[6:7]
	s_waitcnt vmcnt(5)
	v_lshlrev_b32_e32 v12, 16, v60
	v_lshlrev_b32_e32 v15, 16, v61
	v_and_b32_e32 v14, 0xffff0000, v60
	v_add_f32_e32 v5, v5, v12
	v_fmac_f32_e32 v4, v12, v12
	v_pk_mul_f32 v[16:17], v[14:15], v[14:15]
	v_add_f32_e32 v5, v5, v14
	v_add_f32_e32 v4, v16, v4
	v_add_f32_e32 v6, v5, v15
	v_add_f32_e32 v12, v17, v4
	v_lshlrev_b32_e32 v5, 16, v62
	v_and_b32_e32 v4, 0xffff0000, v61
	v_and_b32_e32 v13, 0xffff0000, v62
	v_add_f32_e32 v8, v6, v4
	v_pk_mul_f32 v[6:7], v[4:5], v[4:5]
	v_add_f32_e32 v5, v8, v5
	v_add_f32_e32 v4, v6, v12
	v_lshlrev_b32_e32 v6, 16, v63
	v_mov_b32_e32 v12, v6
	v_add_f32_e32 v14, v7, v4
	v_and_b32_e32 v7, 0xffff0000, v63
	v_pk_mul_f32 v[8:9], v[12:13], v[12:13]
	v_add_f32_e32 v4, v5, v13
	v_add_f32_e32 v5, v9, v14
	v_add_f32_e32 v8, v8, v5
	v_mov_b32_e32 v5, v7
	v_pk_mul_f32 v[12:13], v[6:7], v[6:7]
	v_pk_add_f32 v[4:5], v[4:5], v[6:7]
	v_mov_b32_e32 v9, v7
	v_pk_mov_b32 v[4:5], v[12:13], v[4:5] op_sel:[1,0]
	s_nop 0
	v_pk_add_f32 v[8:9], v[4:5], v[8:9]
	s_waitcnt vmcnt(4)
	v_lshlrev_b32_e32 v10, 16, v64
	v_lshlrev_b32_e32 v13, 16, v65
	v_and_b32_e32 v12, 0xffff0000, v64
	v_add_f32_e32 v9, v9, v10
	v_fmac_f32_e32 v8, v10, v10
	v_pk_mul_f32 v[14:15], v[12:13], v[12:13]
	v_add_f32_e32 v4, v9, v12
	v_add_f32_e32 v8, v14, v8
	v_add_f32_e32 v4, v4, v13
	v_add_f32_e32 v10, v15, v8
	v_lshlrev_b32_e32 v9, 16, v66
	v_and_b32_e32 v8, 0xffff0000, v65
	v_and_b32_e32 v11, 0xffff0000, v66
	v_add_f32_e32 v6, v4, v8
	v_pk_mul_f32 v[4:5], v[8:9], v[8:9]
	v_lshlrev_b32_e32 v8, 16, v67
	v_add_f32_e32 v4, v4, v10
	v_add_f32_e32 v6, v6, v9
	v_mov_b32_e32 v10, v8
	v_add_f32_e32 v5, v5, v4
	v_add_f32_e32 v4, v6, v11
	v_and_b32_e32 v9, 0xffff0000, v67
	v_pk_mul_f32 v[6:7], v[10:11], v[10:11]
	v_pk_mul_f32 v[10:11], v[8:9], v[8:9]
	v_add_f32_e32 v5, v7, v5
	v_add_f32_e32 v6, v6, v5
	v_mov_b32_e32 v5, v9
	v_pk_add_f32 v[4:5], v[4:5], v[8:9]
	v_mov_b32_e32 v7, v9
	v_pk_mov_b32 v[4:5], v[10:11], v[4:5] op_sel:[1,0]
	s_nop 0
	v_pk_add_f32 v[4:5], v[4:5], v[6:7]
	s_waitcnt vmcnt(3)
	v_lshlrev_b32_e32 v12, 16, v68
	v_lshlrev_b32_e32 v15, 16, v69
	v_and_b32_e32 v14, 0xffff0000, v68
	v_add_f32_e32 v5, v5, v12
	v_fmac_f32_e32 v4, v12, v12
	v_pk_mul_f32 v[16:17], v[14:15], v[14:15]
	v_add_f32_e32 v5, v5, v14
	v_add_f32_e32 v4, v16, v4
	v_add_f32_e32 v6, v5, v15
	v_add_f32_e32 v12, v17, v4
	v_lshlrev_b32_e32 v5, 16, v70
	v_and_b32_e32 v4, 0xffff0000, v69
	v_and_b32_e32 v13, 0xffff0000, v70
	v_add_f32_e32 v8, v6, v4
	v_pk_mul_f32 v[6:7], v[4:5], v[4:5]
	v_add_f32_e32 v5, v8, v5
	v_add_f32_e32 v4, v6, v12
	v_lshlrev_b32_e32 v6, 16, v71
	v_mov_b32_e32 v12, v6
	v_add_f32_e32 v14, v7, v4
	v_and_b32_e32 v7, 0xffff0000, v71
	v_pk_mul_f32 v[8:9], v[12:13], v[12:13]
	v_add_f32_e32 v4, v5, v13
	v_add_f32_e32 v5, v9, v14
	v_add_f32_e32 v8, v8, v5
	v_mov_b32_e32 v5, v7
	v_pk_mul_f32 v[12:13], v[6:7], v[6:7]
	v_pk_add_f32 v[4:5], v[4:5], v[6:7]
	v_mov_b32_e32 v9, v7
	v_pk_mov_b32 v[4:5], v[12:13], v[4:5] op_sel:[1,0]
	s_nop 0
	v_pk_add_f32 v[8:9], v[4:5], v[8:9]
	s_waitcnt vmcnt(2)
	v_lshlrev_b32_e32 v10, 16, v72
	v_lshlrev_b32_e32 v13, 16, v73
	v_and_b32_e32 v12, 0xffff0000, v72
	v_add_f32_e32 v9, v9, v10
	v_fmac_f32_e32 v8, v10, v10
	v_pk_mul_f32 v[14:15], v[12:13], v[12:13]
	v_add_f32_e32 v4, v9, v12
	v_add_f32_e32 v8, v14, v8
	v_add_f32_e32 v4, v4, v13
	v_add_f32_e32 v10, v15, v8
	v_lshlrev_b32_e32 v9, 16, v74
	v_and_b32_e32 v8, 0xffff0000, v73
	v_and_b32_e32 v11, 0xffff0000, v74
	v_add_f32_e32 v6, v4, v8
	v_pk_mul_f32 v[4:5], v[8:9], v[8:9]
	v_lshlrev_b32_e32 v8, 16, v75
	v_add_f32_e32 v4, v4, v10
	v_add_f32_e32 v6, v6, v9
	v_mov_b32_e32 v10, v8
	v_add_f32_e32 v5, v5, v4
	v_add_f32_e32 v4, v6, v11
	v_and_b32_e32 v9, 0xffff0000, v75
	v_pk_mul_f32 v[6:7], v[10:11], v[10:11]
	v_pk_mul_f32 v[10:11], v[8:9], v[8:9]
	v_add_f32_e32 v5, v7, v5
	v_add_f32_e32 v6, v6, v5
	v_mov_b32_e32 v5, v9
	v_pk_add_f32 v[4:5], v[4:5], v[8:9]
	v_mov_b32_e32 v7, v9
	v_pk_mov_b32 v[4:5], v[10:11], v[4:5] op_sel:[1,0]
	s_nop 0
	v_pk_add_f32 v[4:5], v[4:5], v[6:7]
	s_waitcnt vmcnt(1)
	v_lshlrev_b32_e32 v12, 16, v76
	v_lshlrev_b32_e32 v15, 16, v77
	v_and_b32_e32 v14, 0xffff0000, v76
	v_add_f32_e32 v5, v5, v12
	v_fmac_f32_e32 v4, v12, v12
	v_pk_mul_f32 v[16:17], v[14:15], v[14:15]
	v_add_f32_e32 v5, v5, v14
	v_add_f32_e32 v4, v16, v4
	v_add_f32_e32 v6, v5, v15
	v_add_f32_e32 v12, v17, v4
	v_lshlrev_b32_e32 v5, 16, v78
	v_and_b32_e32 v4, 0xffff0000, v77
	v_and_b32_e32 v13, 0xffff0000, v78
	v_add_f32_e32 v8, v6, v4
	v_pk_mul_f32 v[6:7], v[4:5], v[4:5]
	v_add_f32_e32 v5, v8, v5
	v_add_f32_e32 v4, v6, v12
	v_lshlrev_b32_e32 v6, 16, v79
	v_mov_b32_e32 v12, v6
	v_add_f32_e32 v14, v7, v4
	v_and_b32_e32 v7, 0xffff0000, v79
	v_pk_mul_f32 v[8:9], v[12:13], v[12:13]
	v_add_f32_e32 v4, v5, v13
	v_add_f32_e32 v5, v9, v14
	v_add_f32_e32 v8, v8, v5
	v_mov_b32_e32 v5, v7
	v_pk_mul_f32 v[12:13], v[6:7], v[6:7]
	v_pk_add_f32 v[4:5], v[4:5], v[6:7]
	v_mov_b32_e32 v9, v7
	v_pk_mov_b32 v[4:5], v[12:13], v[4:5] op_sel:[1,0]
	s_nop 0
	v_pk_add_f32 v[8:9], v[4:5], v[8:9]
	s_waitcnt vmcnt(0)
	v_lshlrev_b32_e32 v10, 16, v80
	v_lshlrev_b32_e32 v13, 16, v81
	v_and_b32_e32 v12, 0xffff0000, v80
	v_add_f32_e32 v9, v9, v10
	v_fmac_f32_e32 v8, v10, v10
	v_pk_mul_f32 v[14:15], v[12:13], v[12:13]
	v_add_f32_e32 v4, v9, v12
	v_add_f32_e32 v8, v14, v8
	v_add_f32_e32 v4, v4, v13
	v_add_f32_e32 v10, v15, v8
	v_lshlrev_b32_e32 v9, 16, v82
	v_and_b32_e32 v8, 0xffff0000, v81
	v_and_b32_e32 v11, 0xffff0000, v82
	v_add_f32_e32 v6, v4, v8
	v_pk_mul_f32 v[4:5], v[8:9], v[8:9]
	v_lshlrev_b32_e32 v8, 16, v83
	v_add_f32_e32 v4, v4, v10
	v_add_f32_e32 v6, v6, v9
	v_mov_b32_e32 v10, v8
	v_add_f32_e32 v5, v5, v4
	v_add_f32_e32 v4, v6, v11
	v_and_b32_e32 v9, 0xffff0000, v83
	v_pk_mul_f32 v[6:7], v[10:11], v[10:11]
	v_pk_mul_f32 v[10:11], v[8:9], v[8:9]
	v_add_f32_e32 v5, v7, v5
	v_add_f32_e32 v6, v6, v5
	v_mov_b32_e32 v5, v9
	v_pk_add_f32 v[4:5], v[4:5], v[8:9]
	v_mov_b32_e32 v7, v9
	v_pk_mov_b32 v[4:5], v[10:11], v[4:5] op_sel:[1,0]
	s_nop 0
	v_pk_add_f32 v[4:5], v[4:5], v[6:7]
	s_cmpk_eq_i32 s8, 0x200
	s_cbranch_scc0 .LBB0_428
	s_nop 0
	v_mov_b32_dpp v3, v5 quad_perm:[1,0,3,2] row_mask:0xf bank_mask:0xf bound_ctrl:1
	v_mov_b32_dpp v2, v4 quad_perm:[1,0,3,2] row_mask:0xf bank_mask:0xf bound_ctrl:1
	v_cmp_eq_u32_e32 vcc, 0, v1
	s_and_saveexec_b64 s[8:9], vcc
	s_cbranch_execz .LBB0_431
	v_pk_add_f32 v[2:3], v[4:5], v[2:3]
	s_mov_b32 s2, 0x3b000000
	v_pk_mul_f32 v[2:3], v[2:3], s[2:3] op_sel_hi:[1,0]
	s_nop 0
	v_fma_f32 v1, -v3, v3, v2
	v_max_f32_e32 v1, 0, v1
	v_add_f32_e32 v1, 0x3727c5ac, v1
	v_mul_f32_e32 v2, 0x4b800000, v1
	v_cmp_gt_f32_e32 vcc, s57, v1
	s_nop 1
	v_cndmask_b32_e32 v1, v1, v2, vcc
	v_rsq_f32_e32 v1, v1
	v_mov_b32_e32 v2, 0x8800
	v_lshl_add_u32 v2, v96, 2, v2
	v_mul_f32_e32 v4, 0x45800000, v1
	v_cndmask_b32_e32 v1, v1, v4, vcc
	ds_write2_b32 v2, v3, v1 offset1:1
